# k-loops of in-proj/ffn1/ffn2: back-edge bookkeeping (counter, pointer selects, LDS read address) computed before the loop-back barrier instead of after it
# baseline (speedup 1.0000x reference)
.Lkrot_37:
	ds_read_b128 v[152:155], v138
	ds_read_b128 v[156:159], v138 offset:1024
	ds_read_b128 v[160:163], v138 offset:2048
	ds_read_b128 v[164:167], v138 offset:3072
	v_add_u32_e32 v138, s64, v150
	s_waitcnt vmcnt(8)
	ds_read_b128 v[168:171], v138
	ds_read_b128 v[172:175], v138 offset:1024
	ds_read_b128 v[184:187], v138 offset:2048
	ds_read_b128 v[188:191], v138 offset:3072
	v_lshl_add_u64 v[138:139], s[54:55], 0, v[142:143]
	s_add_i32 m0, s3, 0xc000
	ds_read_b128 v[192:195], v151
	ds_read_b128 v[196:199], v151 offset:1024
	ds_read_b128 v[200:203], v151 offset:2048
	ds_read_b128 v[204:207], v151 offset:3072
	ds_read_b128 v[208:211], v151 offset:4096
	ds_read_b128 v[212:215], v151 offset:5120
	ds_read_b128 v[216:219], v151 offset:6144
	ds_read_b128 v[220:223], v151 offset:7168
	global_load_lds_dwordx4 v[138:139], off
	v_lshl_add_u64 v[138:139], s[54:55], 0, v[144:145]
	s_add_i32 m0, s3, 0xe000
	s_nop 0
	global_load_lds_dwordx4 v[138:139], off
	s_waitcnt vmcnt(8)
	s_waitcnt lgkmcnt(0)
	s_barrier
	s_setprio 1
	s_waitcnt lgkmcnt(0)
	v_mfma_f32_16x16x32_bf16 v[126:129], v[152:155], v[192:195], v[126:129]
	v_mfma_f32_16x16x32_bf16 v[122:125], v[160:163], v[192:195], v[122:125]
	v_mfma_f32_16x16x32_bf16 v[110:113], v[152:155], v[200:203], v[110:113]
	v_mfma_f32_16x16x32_bf16 v[106:109], v[160:163], v[200:203], v[106:109]
	v_mfma_f32_16x16x32_bf16 v[94:97], v[152:155], v[208:211], v[94:97]
	v_mfma_f32_16x16x32_bf16 v[90:93], v[160:163], v[208:211], v[90:93]
	v_mfma_f32_16x16x32_bf16 v[78:81], v[152:155], v[216:219], v[78:81]
	v_mfma_f32_16x16x32_bf16 v[74:77], v[160:163], v[216:219], v[74:77]
	v_mfma_f32_16x16x32_bf16 v[126:129], v[156:159], v[196:199], v[126:129]
	v_mfma_f32_16x16x32_bf16 v[122:125], v[164:167], v[196:199], v[122:125]
	v_mfma_f32_16x16x32_bf16 v[110:113], v[156:159], v[204:207], v[110:113]
	v_mfma_f32_16x16x32_bf16 v[106:109], v[164:167], v[204:207], v[106:109]
	v_mfma_f32_16x16x32_bf16 v[94:97], v[156:159], v[212:215], v[94:97]
	v_mfma_f32_16x16x32_bf16 v[90:93], v[164:167], v[212:215], v[90:93]
	v_mfma_f32_16x16x32_bf16 v[78:81], v[156:159], v[220:223], v[78:81]
	v_mfma_f32_16x16x32_bf16 v[74:77], v[164:167], v[220:223], v[74:77]
	s_setprio 0
	s_setprio 1
	v_mfma_f32_16x16x32_bf16 v[118:121], v[168:171], v[192:195], v[118:121]
	v_mfma_f32_16x16x32_bf16 v[114:117], v[184:187], v[192:195], v[114:117]
	v_mfma_f32_16x16x32_bf16 v[102:105], v[168:171], v[200:203], v[102:105]
	v_mfma_f32_16x16x32_bf16 v[98:101], v[184:187], v[200:203], v[98:101]
	v_mfma_f32_16x16x32_bf16 v[86:89], v[168:171], v[208:211], v[86:89]
	v_mfma_f32_16x16x32_bf16 v[82:85], v[184:187], v[208:211], v[82:85]
	v_mfma_f32_16x16x32_bf16 v[70:73], v[168:171], v[216:219], v[70:73]
	v_mfma_f32_16x16x32_bf16 v[66:69], v[184:187], v[216:219], v[66:69]
	v_mfma_f32_16x16x32_bf16 v[118:121], v[172:175], v[196:199], v[118:121]
	v_mfma_f32_16x16x32_bf16 v[114:117], v[188:191], v[196:199], v[114:117]
	v_mfma_f32_16x16x32_bf16 v[102:105], v[172:175], v[204:207], v[102:105]
	v_mfma_f32_16x16x32_bf16 v[98:101], v[188:191], v[204:207], v[98:101]
	v_mfma_f32_16x16x32_bf16 v[86:89], v[172:175], v[212:215], v[86:89]
	v_mfma_f32_16x16x32_bf16 v[82:85], v[188:191], v[212:215], v[82:85]
	v_mfma_f32_16x16x32_bf16 v[70:73], v[172:175], v[220:223], v[70:73]
	v_mfma_f32_16x16x32_bf16 v[66:69], v[188:191], v[220:223], v[66:69]
	s_setprio 0
	s_barrier
	s_add_i32 s61, s61, s2
	v_lshl_add_u64 v[138:139], s[4:5], 0, v[134:135]
	s_mov_b32 m0, s61
	ds_read_b128 v[192:195], v151 offset:16384
	ds_read_b128 v[196:199], v151 offset:17408
	ds_read_b128 v[200:203], v151 offset:18432
	ds_read_b128 v[204:207], v151 offset:19456
	ds_read_b128 v[208:211], v151 offset:20480
	ds_read_b128 v[212:215], v151 offset:21504
	ds_read_b128 v[216:219], v151 offset:22528
	ds_read_b128 v[220:223], v151 offset:23552
	global_load_lds_dwordx4 v[138:139], off
	s_add_i32 m0, s61, 0x2000
	s_add_u32 s62, s4, 0x40000
	v_lshl_add_u64 v[148:149], s[4:5], 0, v[130:131]
	s_addc_u32 s63, s5, 0
	s_add_i32 s61, s64, s2
	global_load_lds_dwordx4 v[148:149], off
	v_lshl_add_u64 v[182:183], s[62:63], 0, v[134:135]
	s_mov_b32 m0, s61
	v_lshl_add_u64 v[224:225], s[56:57], 0, v[132:133]
	global_load_lds_dwordx4 v[182:183], off
	v_lshl_add_u64 v[182:183], s[62:63], 0, v[130:131]
	s_add_i32 m0, s61, 0x2000
	s_nop 0
	global_load_lds_dwordx4 v[182:183], off
	v_lshl_add_u64 v[182:183], s[56:57], 0, v[136:137]
	s_mov_b32 m0, s3
	s_nop 0
	global_load_lds_dwordx4 v[182:183], off
	s_mov_b32 m0, s10
	s_nop 0
	global_load_lds_dwordx4 v[224:225], off
	s_waitcnt vmcnt(8)
	s_waitcnt lgkmcnt(0)
	s_barrier
	s_setprio 1
	s_waitcnt lgkmcnt(0)
	v_mfma_f32_16x16x32_bf16 v[60:63], v[152:155], v[192:195], v[60:63]
	v_mfma_f32_16x16x32_bf16 v[56:59], v[160:163], v[192:195], v[56:59]
	v_mfma_f32_16x16x32_bf16 v[44:47], v[152:155], v[200:203], v[44:47]
	v_mfma_f32_16x16x32_bf16 v[40:43], v[160:163], v[200:203], v[40:43]
	v_mfma_f32_16x16x32_bf16 v[28:31], v[152:155], v[208:211], v[28:31]
	v_mfma_f32_16x16x32_bf16 v[24:27], v[160:163], v[208:211], v[24:27]
	v_mfma_f32_16x16x32_bf16 v[12:15], v[152:155], v[216:219], v[12:15]
	v_mfma_f32_16x16x32_bf16 v[8:11], v[160:163], v[216:219], v[8:11]
	v_mfma_f32_16x16x32_bf16 v[60:63], v[156:159], v[196:199], v[60:63]
	v_mfma_f32_16x16x32_bf16 v[56:59], v[164:167], v[196:199], v[56:59]
	v_mfma_f32_16x16x32_bf16 v[44:47], v[156:159], v[204:207], v[44:47]
	v_mfma_f32_16x16x32_bf16 v[40:43], v[164:167], v[204:207], v[40:43]
	v_mfma_f32_16x16x32_bf16 v[28:31], v[156:159], v[212:215], v[28:31]
	v_mfma_f32_16x16x32_bf16 v[24:27], v[164:167], v[212:215], v[24:27]
	v_mfma_f32_16x16x32_bf16 v[12:15], v[156:159], v[220:223], v[12:15]
	v_mfma_f32_16x16x32_bf16 v[8:11], v[164:167], v[220:223], v[8:11]
	s_setprio 0
	s_setprio 1
	v_mfma_f32_16x16x32_bf16 v[52:55], v[168:171], v[192:195], v[52:55]
	v_mfma_f32_16x16x32_bf16 v[48:51], v[184:187], v[192:195], v[48:51]
	v_mfma_f32_16x16x32_bf16 v[36:39], v[168:171], v[200:203], v[36:39]
	v_mfma_f32_16x16x32_bf16 v[32:35], v[184:187], v[200:203], v[32:35]
	v_mfma_f32_16x16x32_bf16 v[20:23], v[168:171], v[208:211], v[20:23]
	v_mfma_f32_16x16x32_bf16 v[16:19], v[184:187], v[208:211], v[16:19]
	v_mfma_f32_16x16x32_bf16 v[4:7], v[168:171], v[216:219], v[4:7]
	v_mfma_f32_16x16x32_bf16 v[0:3], v[184:187], v[216:219], v[0:3]
	v_mfma_f32_16x16x32_bf16 v[52:55], v[172:175], v[196:199], v[52:55]
	v_mfma_f32_16x16x32_bf16 v[48:51], v[188:191], v[196:199], v[48:51]
	v_mfma_f32_16x16x32_bf16 v[36:39], v[172:175], v[204:207], v[36:39]
	v_mfma_f32_16x16x32_bf16 v[32:35], v[188:191], v[204:207], v[32:35]
	v_mfma_f32_16x16x32_bf16 v[20:23], v[172:175], v[212:215], v[20:23]
	v_mfma_f32_16x16x32_bf16 v[16:19], v[188:191], v[212:215], v[16:19]
	v_mfma_f32_16x16x32_bf16 v[4:7], v[172:175], v[220:223], v[4:7]
	v_mfma_f32_16x16x32_bf16 v[0:3], v[188:191], v[220:223], v[0:3]
	s_setprio 0
	s_barrier
	s_add_i32 s61, 0, 0x18000
	v_add_u32_e32 v147, s61, v150
	s_add_i32 s62, 0, 0x1c000
	ds_read_b128 v[152:155], v147
	ds_read_b128 v[156:159], v147 offset:1024
	ds_read_b128 v[160:163], v147 offset:2048
	ds_read_b128 v[164:167], v147 offset:3072
	v_add_u32_e32 v147, s62, v150
	ds_read_b128 v[168:171], v147
	ds_read_b128 v[172:175], v147 offset:1024
	ds_read_b128 v[184:187], v147 offset:2048
	ds_read_b128 v[188:191], v147 offset:3072
	s_add_u32 s56, s56, 0x40000
	s_addc_u32 s57, s57, 0
	s_mov_b32 m0, s18
	v_lshl_add_u64 v[226:227], s[56:57], 0, v[136:137]
	ds_read_b128 v[192:195], v151 offset:32768
	ds_read_b128 v[196:199], v151 offset:33792
	ds_read_b128 v[200:203], v151 offset:34816
	ds_read_b128 v[204:207], v151 offset:35840
	ds_read_b128 v[208:211], v151 offset:36864
	ds_read_b128 v[212:215], v151 offset:37888
	ds_read_b128 v[216:219], v151 offset:38912
	ds_read_b128 v[220:223], v151 offset:39936
	global_load_lds_dwordx4 v[226:227], off
	v_lshl_add_u64 v[226:227], s[56:57], 0, v[132:133]
	s_mov_b32 m0, s19
	s_nop 0
	global_load_lds_dwordx4 v[226:227], off
	s_waitcnt vmcnt(8)
	s_waitcnt lgkmcnt(0)
	s_barrier
	s_setprio 1
	s_waitcnt lgkmcnt(0)
	v_mfma_f32_16x16x32_bf16 v[126:129], v[152:155], v[192:195], v[126:129]
	v_mfma_f32_16x16x32_bf16 v[122:125], v[160:163], v[192:195], v[122:125]
	v_mfma_f32_16x16x32_bf16 v[110:113], v[152:155], v[200:203], v[110:113]
	v_mfma_f32_16x16x32_bf16 v[106:109], v[160:163], v[200:203], v[106:109]
	v_mfma_f32_16x16x32_bf16 v[94:97], v[152:155], v[208:211], v[94:97]
	v_mfma_f32_16x16x32_bf16 v[90:93], v[160:163], v[208:211], v[90:93]
	v_mfma_f32_16x16x32_bf16 v[78:81], v[152:155], v[216:219], v[78:81]
	v_mfma_f32_16x16x32_bf16 v[74:77], v[160:163], v[216:219], v[74:77]
	v_mfma_f32_16x16x32_bf16 v[126:129], v[156:159], v[196:199], v[126:129]
	v_mfma_f32_16x16x32_bf16 v[122:125], v[164:167], v[196:199], v[122:125]
	v_mfma_f32_16x16x32_bf16 v[110:113], v[156:159], v[204:207], v[110:113]
	v_mfma_f32_16x16x32_bf16 v[106:109], v[164:167], v[204:207], v[106:109]
	v_mfma_f32_16x16x32_bf16 v[94:97], v[156:159], v[212:215], v[94:97]
	v_mfma_f32_16x16x32_bf16 v[90:93], v[164:167], v[212:215], v[90:93]
	v_mfma_f32_16x16x32_bf16 v[78:81], v[156:159], v[220:223], v[78:81]
	v_mfma_f32_16x16x32_bf16 v[74:77], v[164:167], v[220:223], v[74:77]
	s_setprio 0
	s_setprio 1
	v_mfma_f32_16x16x32_bf16 v[118:121], v[168:171], v[192:195], v[118:121]
	v_mfma_f32_16x16x32_bf16 v[114:117], v[184:187], v[192:195], v[114:117]
	v_mfma_f32_16x16x32_bf16 v[102:105], v[168:171], v[200:203], v[102:105]
	v_mfma_f32_16x16x32_bf16 v[98:101], v[184:187], v[200:203], v[98:101]
	v_mfma_f32_16x16x32_bf16 v[86:89], v[168:171], v[208:211], v[86:89]
	v_mfma_f32_16x16x32_bf16 v[82:85], v[184:187], v[208:211], v[82:85]
	v_mfma_f32_16x16x32_bf16 v[70:73], v[168:171], v[216:219], v[70:73]
	v_mfma_f32_16x16x32_bf16 v[66:69], v[184:187], v[216:219], v[66:69]
	v_mfma_f32_16x16x32_bf16 v[118:121], v[172:175], v[196:199], v[118:121]
	v_mfma_f32_16x16x32_bf16 v[114:117], v[188:191], v[196:199], v[114:117]
	v_mfma_f32_16x16x32_bf16 v[102:105], v[172:175], v[204:207], v[102:105]
	v_mfma_f32_16x16x32_bf16 v[98:101], v[188:191], v[204:207], v[98:101]
	v_mfma_f32_16x16x32_bf16 v[86:89], v[172:175], v[212:215], v[86:89]
	v_mfma_f32_16x16x32_bf16 v[82:85], v[188:191], v[212:215], v[82:85]
	v_mfma_f32_16x16x32_bf16 v[70:73], v[172:175], v[220:223], v[70:73]
	v_mfma_f32_16x16x32_bf16 v[66:69], v[188:191], v[220:223], v[66:69]
	s_setprio 0
	s_barrier
	s_add_i32 s56, s61, s2
	v_lshl_add_u64 v[138:139], v[138:139], 0, s[14:15]
	s_mov_b32 m0, s56
	ds_read_b128 v[192:195], v151 offset:49152
	ds_read_b128 v[196:199], v151 offset:50176
	ds_read_b128 v[200:203], v151 offset:51200
	ds_read_b128 v[204:207], v151 offset:52224
	ds_read_b128 v[208:211], v151 offset:53248
	ds_read_b128 v[212:215], v151 offset:54272
	ds_read_b128 v[216:219], v151 offset:55296
	ds_read_b128 v[220:223], v151 offset:56320
	global_load_lds_dwordx4 v[138:139], off
	s_add_i32 m0, s56, 0x2000
	s_add_u32 s4, s4, 0x40080
	v_lshl_add_u64 v[138:139], v[148:149], 0, s[14:15]
	s_addc_u32 s5, s5, 0
	s_add_i32 s56, s62, s2
	global_load_lds_dwordx4 v[138:139], off
	v_lshl_add_u64 v[138:139], s[4:5], 0, v[134:135]
	s_mov_b32 m0, s56
	s_nop 0
	global_load_lds_dwordx4 v[138:139], off
	v_lshl_add_u64 v[138:139], s[4:5], 0, v[130:131]
	s_add_i32 m0, s56, 0x2000
	s_nop 0
	global_load_lds_dwordx4 v[138:139], off
	v_lshl_add_u64 v[138:139], v[182:183], 0, s[14:15]
	s_mov_b32 m0, s20
	s_nop 0
	global_load_lds_dwordx4 v[138:139], off
	v_lshl_add_u64 v[138:139], v[224:225], 0, s[14:15]
	s_mov_b32 m0, s21
	s_nop 0
	global_load_lds_dwordx4 v[138:139], off
	s_waitcnt vmcnt(8)
	s_waitcnt lgkmcnt(0)
	s_barrier
	s_setprio 1
	s_waitcnt lgkmcnt(0)
	v_mfma_f32_16x16x32_bf16 v[60:63], v[152:155], v[192:195], v[60:63]
	v_mfma_f32_16x16x32_bf16 v[56:59], v[160:163], v[192:195], v[56:59]
	v_mfma_f32_16x16x32_bf16 v[44:47], v[152:155], v[200:203], v[44:47]
	v_mfma_f32_16x16x32_bf16 v[40:43], v[160:163], v[200:203], v[40:43]
	v_mfma_f32_16x16x32_bf16 v[28:31], v[152:155], v[208:211], v[28:31]
	v_mfma_f32_16x16x32_bf16 v[24:27], v[160:163], v[208:211], v[24:27]
	v_mfma_f32_16x16x32_bf16 v[12:15], v[152:155], v[216:219], v[12:15]
	v_mfma_f32_16x16x32_bf16 v[8:11], v[160:163], v[216:219], v[8:11]
	v_mfma_f32_16x16x32_bf16 v[60:63], v[156:159], v[196:199], v[60:63]
	v_mfma_f32_16x16x32_bf16 v[56:59], v[164:167], v[196:199], v[56:59]
	v_mfma_f32_16x16x32_bf16 v[44:47], v[156:159], v[204:207], v[44:47]
	v_mfma_f32_16x16x32_bf16 v[40:43], v[164:167], v[204:207], v[40:43]
	v_mfma_f32_16x16x32_bf16 v[28:31], v[156:159], v[212:215], v[28:31]
	v_mfma_f32_16x16x32_bf16 v[24:27], v[164:167], v[212:215], v[24:27]
	v_mfma_f32_16x16x32_bf16 v[12:15], v[156:159], v[220:223], v[12:15]
	v_mfma_f32_16x16x32_bf16 v[8:11], v[164:167], v[220:223], v[8:11]
	s_setprio 0
	s_setprio 1
	v_mfma_f32_16x16x32_bf16 v[52:55], v[168:171], v[192:195], v[52:55]
	v_mfma_f32_16x16x32_bf16 v[48:51], v[184:187], v[192:195], v[48:51]
	v_mfma_f32_16x16x32_bf16 v[36:39], v[168:171], v[200:203], v[36:39]
	v_mfma_f32_16x16x32_bf16 v[32:35], v[184:187], v[200:203], v[32:35]
	v_mfma_f32_16x16x32_bf16 v[20:23], v[168:171], v[208:211], v[20:23]
	v_mfma_f32_16x16x32_bf16 v[16:19], v[184:187], v[208:211], v[16:19]
	v_mfma_f32_16x16x32_bf16 v[4:7], v[168:171], v[216:219], v[4:7]
	v_mfma_f32_16x16x32_bf16 v[0:3], v[184:187], v[216:219], v[0:3]
	v_mfma_f32_16x16x32_bf16 v[52:55], v[172:175], v[196:199], v[52:55]
	v_mfma_f32_16x16x32_bf16 v[48:51], v[188:191], v[196:199], v[48:51]
	v_mfma_f32_16x16x32_bf16 v[36:39], v[172:175], v[204:207], v[36:39]
	v_mfma_f32_16x16x32_bf16 v[32:35], v[188:191], v[204:207], v[32:35]
	v_mfma_f32_16x16x32_bf16 v[20:23], v[172:175], v[212:215], v[20:23]
	v_mfma_f32_16x16x32_bf16 v[16:19], v[188:191], v[212:215], v[16:19]
	v_mfma_f32_16x16x32_bf16 v[4:7], v[172:175], v[220:223], v[4:7]
	v_mfma_f32_16x16x32_bf16 v[0:3], v[188:191], v[220:223], v[0:3]
	s_setprio 0
	s_add_i32 s60, s60, 2
	s_add_u32 s54, s54, 0x100
	s_addc_u32 s55, s55, 0
	s_add_u32 s58, s58, 0x100
	s_addc_u32 s59, s59, 0
	s_add_u32 s4, s54, 0xfffc0080
	s_addc_u32 s5, s55, -1
	s_add_i32 s61, 0, 0x10000
	s_cmp_eq_u32 s60, 12
	s_cselect_b32 s57, s29, s5
	s_cselect_b32 s56, s33, s4
	v_add_u32_e32 v138, s61, v150
	s_cselect_b32 s5, s47, s59
	s_cselect_b32 s4, s49, s58
	s_add_i32 s64, 0, 0x14000
	s_cmp_gt_u32 s60, 13
	s_barrier
	s_cbranch_scc0 .Lkrot_37
	s_and_b64 vcc, exec, s[40:41]
	s_cbranch_vccz .LBB0_40
	s_barrier

.Lkrot_146:
	ds_read_b128 v[148:151], v138
	ds_read_b128 v[184:187], v138 offset:1024
	ds_read_b128 v[188:191], v138 offset:2048
	ds_read_b128 v[192:195], v138 offset:3072
	v_add_u32_e32 v138, s64, v173
	ds_read_b128 v[196:199], v138
	ds_read_b128 v[200:203], v138 offset:1024
	ds_read_b128 v[204:207], v138 offset:2048
	ds_read_b128 v[208:211], v138 offset:3072
	v_lshl_add_u64 v[138:139], s[54:55], 0, v[144:145]
	s_add_i32 m0, s3, 0xc000
	ds_read_b128 v[212:215], v174
	ds_read_b128 v[216:219], v174 offset:1024
	ds_read_b128 v[220:223], v174 offset:2048
	ds_read_b128 v[224:227], v174 offset:3072
	ds_read_b128 v[228:231], v174 offset:4096
	ds_read_b128 v[232:235], v174 offset:5120
	ds_read_b128 v[236:239], v174 offset:6144
	ds_read_b128 v[240:243], v174 offset:7168
	global_load_lds_dwordx4 v[138:139], off
	v_lshl_add_u64 v[138:139], s[54:55], 0, v[146:147]
	s_add_i32 m0, s3, 0xe000
	s_nop 0
	global_load_lds_dwordx4 v[138:139], off
	s_waitcnt vmcnt(8)
	s_waitcnt lgkmcnt(0)
	s_barrier
	s_setprio 1
	s_waitcnt lgkmcnt(0)
	v_mfma_f32_16x16x32_bf16 v[126:129], v[148:151], v[212:215], v[126:129]
	v_mfma_f32_16x16x32_bf16 v[122:125], v[188:191], v[212:215], v[122:125]
	v_mfma_f32_16x16x32_bf16 v[110:113], v[148:151], v[220:223], v[110:113]
	v_mfma_f32_16x16x32_bf16 v[106:109], v[188:191], v[220:223], v[106:109]
	v_mfma_f32_16x16x32_bf16 v[94:97], v[148:151], v[228:231], v[94:97]
	v_mfma_f32_16x16x32_bf16 v[90:93], v[188:191], v[228:231], v[90:93]
	v_mfma_f32_16x16x32_bf16 v[78:81], v[148:151], v[236:239], v[78:81]
	v_mfma_f32_16x16x32_bf16 v[74:77], v[188:191], v[236:239], v[74:77]
	v_mfma_f32_16x16x32_bf16 v[126:129], v[184:187], v[216:219], v[126:129]
	v_mfma_f32_16x16x32_bf16 v[122:125], v[192:195], v[216:219], v[122:125]
	v_mfma_f32_16x16x32_bf16 v[110:113], v[184:187], v[224:227], v[110:113]
	v_mfma_f32_16x16x32_bf16 v[106:109], v[192:195], v[224:227], v[106:109]
	v_mfma_f32_16x16x32_bf16 v[94:97], v[184:187], v[232:235], v[94:97]
	v_mfma_f32_16x16x32_bf16 v[90:93], v[192:195], v[232:235], v[90:93]
	v_mfma_f32_16x16x32_bf16 v[78:81], v[184:187], v[240:243], v[78:81]
	v_mfma_f32_16x16x32_bf16 v[74:77], v[192:195], v[240:243], v[74:77]
	s_setprio 0
	s_setprio 1
	v_mfma_f32_16x16x32_bf16 v[118:121], v[196:199], v[212:215], v[118:121]
	v_mfma_f32_16x16x32_bf16 v[114:117], v[204:207], v[212:215], v[114:117]
	v_mfma_f32_16x16x32_bf16 v[102:105], v[196:199], v[220:223], v[102:105]
	v_mfma_f32_16x16x32_bf16 v[98:101], v[204:207], v[220:223], v[98:101]
	v_mfma_f32_16x16x32_bf16 v[86:89], v[196:199], v[228:231], v[86:89]
	v_mfma_f32_16x16x32_bf16 v[82:85], v[204:207], v[228:231], v[82:85]
	v_mfma_f32_16x16x32_bf16 v[70:73], v[196:199], v[236:239], v[70:73]
	v_mfma_f32_16x16x32_bf16 v[66:69], v[204:207], v[236:239], v[66:69]
	v_mfma_f32_16x16x32_bf16 v[118:121], v[200:203], v[216:219], v[118:121]
	v_mfma_f32_16x16x32_bf16 v[114:117], v[208:211], v[216:219], v[114:117]
	v_mfma_f32_16x16x32_bf16 v[102:105], v[200:203], v[224:227], v[102:105]
	v_mfma_f32_16x16x32_bf16 v[98:101], v[208:211], v[224:227], v[98:101]
	v_mfma_f32_16x16x32_bf16 v[86:89], v[200:203], v[232:235], v[86:89]
	v_mfma_f32_16x16x32_bf16 v[82:85], v[208:211], v[232:235], v[82:85]
	v_mfma_f32_16x16x32_bf16 v[70:73], v[200:203], v[240:243], v[70:73]
	v_mfma_f32_16x16x32_bf16 v[66:69], v[208:211], v[240:243], v[66:69]
	s_setprio 0
	s_barrier
	s_add_i32 s62, s62, s2
	v_lshl_add_u64 v[138:139], s[4:5], 0, v[134:135]
	s_mov_b32 m0, s62
	ds_read_b128 v[212:215], v174 offset:16384
	ds_read_b128 v[216:219], v174 offset:17408
	ds_read_b128 v[220:223], v174 offset:18432
	ds_read_b128 v[224:227], v174 offset:19456
	ds_read_b128 v[228:231], v174 offset:20480
	ds_read_b128 v[232:235], v174 offset:21504
	ds_read_b128 v[236:239], v174 offset:22528
	ds_read_b128 v[240:243], v174 offset:23552
	global_load_lds_dwordx4 v[138:139], off
	s_add_i32 m0, s62, 0x2000
	s_add_u32 s62, s4, 0x100000
	v_lshl_add_u64 v[182:183], s[4:5], 0, v[130:131]
	s_addc_u32 s63, s5, 0
	s_add_i32 s64, s64, s2
	global_load_lds_dwordx4 v[182:183], off
	v_lshl_add_u64 v[244:245], s[62:63], 0, v[134:135]
	s_mov_b32 m0, s64
	v_lshl_add_u64 v[246:247], s[56:57], 0, v[132:133]
	global_load_lds_dwordx4 v[244:245], off
	v_lshl_add_u64 v[244:245], s[62:63], 0, v[130:131]
	s_add_i32 m0, s64, 0x2000
	s_nop 0
	global_load_lds_dwordx4 v[244:245], off
	v_lshl_add_u64 v[244:245], s[56:57], 0, v[136:137]
	s_mov_b32 m0, s3
	s_nop 0
	global_load_lds_dwordx4 v[244:245], off
	s_mov_b32 m0, s10
	s_nop 0
	global_load_lds_dwordx4 v[246:247], off
	s_waitcnt vmcnt(8)
	s_waitcnt lgkmcnt(0)
	s_barrier
	s_setprio 1
	s_waitcnt lgkmcnt(0)
	v_mfma_f32_16x16x32_bf16 v[60:63], v[148:151], v[212:215], v[60:63]
	v_mfma_f32_16x16x32_bf16 v[56:59], v[188:191], v[212:215], v[56:59]
	v_mfma_f32_16x16x32_bf16 v[44:47], v[148:151], v[220:223], v[44:47]
	v_mfma_f32_16x16x32_bf16 v[40:43], v[188:191], v[220:223], v[40:43]
	v_mfma_f32_16x16x32_bf16 v[28:31], v[148:151], v[228:231], v[28:31]
	v_mfma_f32_16x16x32_bf16 v[24:27], v[188:191], v[228:231], v[24:27]
	v_mfma_f32_16x16x32_bf16 v[12:15], v[148:151], v[236:239], v[12:15]
	v_mfma_f32_16x16x32_bf16 v[8:11], v[188:191], v[236:239], v[8:11]
	v_mfma_f32_16x16x32_bf16 v[60:63], v[184:187], v[216:219], v[60:63]
	v_mfma_f32_16x16x32_bf16 v[56:59], v[192:195], v[216:219], v[56:59]
	v_mfma_f32_16x16x32_bf16 v[44:47], v[184:187], v[224:227], v[44:47]
	v_mfma_f32_16x16x32_bf16 v[40:43], v[192:195], v[224:227], v[40:43]
	v_mfma_f32_16x16x32_bf16 v[28:31], v[184:187], v[232:235], v[28:31]
	v_mfma_f32_16x16x32_bf16 v[24:27], v[192:195], v[232:235], v[24:27]
	v_mfma_f32_16x16x32_bf16 v[12:15], v[184:187], v[240:243], v[12:15]
	v_mfma_f32_16x16x32_bf16 v[8:11], v[192:195], v[240:243], v[8:11]
	s_setprio 0
	s_setprio 1
	v_mfma_f32_16x16x32_bf16 v[52:55], v[196:199], v[212:215], v[52:55]
	v_mfma_f32_16x16x32_bf16 v[48:51], v[204:207], v[212:215], v[48:51]
	v_mfma_f32_16x16x32_bf16 v[36:39], v[196:199], v[220:223], v[36:39]
	v_mfma_f32_16x16x32_bf16 v[32:35], v[204:207], v[220:223], v[32:35]
	v_mfma_f32_16x16x32_bf16 v[20:23], v[196:199], v[228:231], v[20:23]
	v_mfma_f32_16x16x32_bf16 v[16:19], v[204:207], v[228:231], v[16:19]
	v_mfma_f32_16x16x32_bf16 v[4:7], v[196:199], v[236:239], v[4:7]
	v_mfma_f32_16x16x32_bf16 v[0:3], v[204:207], v[236:239], v[0:3]
	v_mfma_f32_16x16x32_bf16 v[52:55], v[200:203], v[216:219], v[52:55]
	v_mfma_f32_16x16x32_bf16 v[48:51], v[208:211], v[216:219], v[48:51]
	v_mfma_f32_16x16x32_bf16 v[36:39], v[200:203], v[224:227], v[36:39]
	v_mfma_f32_16x16x32_bf16 v[32:35], v[208:211], v[224:227], v[32:35]
	v_mfma_f32_16x16x32_bf16 v[20:23], v[200:203], v[232:235], v[20:23]
	v_mfma_f32_16x16x32_bf16 v[16:19], v[208:211], v[232:235], v[16:19]
	v_mfma_f32_16x16x32_bf16 v[4:7], v[200:203], v[240:243], v[4:7]
	v_mfma_f32_16x16x32_bf16 v[0:3], v[208:211], v[240:243], v[0:3]
	s_setprio 0
	s_barrier
	s_add_i32 s62, 0, 0x18000
	v_add_u32_e32 v175, s62, v173
	s_add_i32 s63, 0, 0x1c000
	ds_read_b128 v[148:151], v175
	ds_read_b128 v[184:187], v175 offset:1024
	ds_read_b128 v[188:191], v175 offset:2048
	ds_read_b128 v[192:195], v175 offset:3072
	v_add_u32_e32 v175, s63, v173
	ds_read_b128 v[196:199], v175
	ds_read_b128 v[200:203], v175 offset:1024
	ds_read_b128 v[204:207], v175 offset:2048
	ds_read_b128 v[208:211], v175 offset:3072
	s_add_u32 s56, s56, 0x100000
	s_addc_u32 s57, s57, 0
	s_mov_b32 m0, s18
	v_lshl_add_u64 v[248:249], s[56:57], 0, v[136:137]
	ds_read_b128 v[212:215], v174 offset:32768
	ds_read_b128 v[216:219], v174 offset:33792
	ds_read_b128 v[220:223], v174 offset:34816
	ds_read_b128 v[224:227], v174 offset:35840
	ds_read_b128 v[228:231], v174 offset:36864
	ds_read_b128 v[232:235], v174 offset:37888
	ds_read_b128 v[236:239], v174 offset:38912
	ds_read_b128 v[240:243], v174 offset:39936
	global_load_lds_dwordx4 v[248:249], off
	v_lshl_add_u64 v[248:249], s[56:57], 0, v[132:133]
	s_mov_b32 m0, s19
	s_nop 0
	global_load_lds_dwordx4 v[248:249], off
	s_waitcnt vmcnt(8)
	s_waitcnt lgkmcnt(0)
	s_barrier
	s_setprio 1
	s_waitcnt lgkmcnt(0)
	v_mfma_f32_16x16x32_bf16 v[126:129], v[148:151], v[212:215], v[126:129]
	v_mfma_f32_16x16x32_bf16 v[122:125], v[188:191], v[212:215], v[122:125]
	v_mfma_f32_16x16x32_bf16 v[110:113], v[148:151], v[220:223], v[110:113]
	v_mfma_f32_16x16x32_bf16 v[106:109], v[188:191], v[220:223], v[106:109]
	v_mfma_f32_16x16x32_bf16 v[94:97], v[148:151], v[228:231], v[94:97]
	v_mfma_f32_16x16x32_bf16 v[90:93], v[188:191], v[228:231], v[90:93]
	v_mfma_f32_16x16x32_bf16 v[78:81], v[148:151], v[236:239], v[78:81]
	v_mfma_f32_16x16x32_bf16 v[74:77], v[188:191], v[236:239], v[74:77]
	v_mfma_f32_16x16x32_bf16 v[126:129], v[184:187], v[216:219], v[126:129]
	v_mfma_f32_16x16x32_bf16 v[122:125], v[192:195], v[216:219], v[122:125]
	v_mfma_f32_16x16x32_bf16 v[110:113], v[184:187], v[224:227], v[110:113]
	v_mfma_f32_16x16x32_bf16 v[106:109], v[192:195], v[224:227], v[106:109]
	v_mfma_f32_16x16x32_bf16 v[94:97], v[184:187], v[232:235], v[94:97]
	v_mfma_f32_16x16x32_bf16 v[90:93], v[192:195], v[232:235], v[90:93]
	v_mfma_f32_16x16x32_bf16 v[78:81], v[184:187], v[240:243], v[78:81]
	v_mfma_f32_16x16x32_bf16 v[74:77], v[192:195], v[240:243], v[74:77]
	s_setprio 0
	s_setprio 1
	v_mfma_f32_16x16x32_bf16 v[118:121], v[196:199], v[212:215], v[118:121]
	v_mfma_f32_16x16x32_bf16 v[114:117], v[204:207], v[212:215], v[114:117]
	v_mfma_f32_16x16x32_bf16 v[102:105], v[196:199], v[220:223], v[102:105]
	v_mfma_f32_16x16x32_bf16 v[98:101], v[204:207], v[220:223], v[98:101]
	v_mfma_f32_16x16x32_bf16 v[86:89], v[196:199], v[228:231], v[86:89]
	v_mfma_f32_16x16x32_bf16 v[82:85], v[204:207], v[228:231], v[82:85]
	v_mfma_f32_16x16x32_bf16 v[70:73], v[196:199], v[236:239], v[70:73]
	v_mfma_f32_16x16x32_bf16 v[66:69], v[204:207], v[236:239], v[66:69]
	v_mfma_f32_16x16x32_bf16 v[118:121], v[200:203], v[216:219], v[118:121]
	v_mfma_f32_16x16x32_bf16 v[114:117], v[208:211], v[216:219], v[114:117]
	v_mfma_f32_16x16x32_bf16 v[102:105], v[200:203], v[224:227], v[102:105]
	v_mfma_f32_16x16x32_bf16 v[98:101], v[208:211], v[224:227], v[98:101]
	v_mfma_f32_16x16x32_bf16 v[86:89], v[200:203], v[232:235], v[86:89]
	v_mfma_f32_16x16x32_bf16 v[82:85], v[208:211], v[232:235], v[82:85]
	v_mfma_f32_16x16x32_bf16 v[70:73], v[200:203], v[240:243], v[70:73]
	v_mfma_f32_16x16x32_bf16 v[66:69], v[208:211], v[240:243], v[66:69]
	s_setprio 0
	s_barrier
	s_add_i32 s56, s62, s2
	v_lshl_add_u64 v[138:139], v[138:139], 0, s[14:15]
	s_mov_b32 m0, s56
	ds_read_b128 v[212:215], v174 offset:49152
	ds_read_b128 v[216:219], v174 offset:50176
	ds_read_b128 v[220:223], v174 offset:51200
	ds_read_b128 v[224:227], v174 offset:52224
	ds_read_b128 v[228:231], v174 offset:53248
	ds_read_b128 v[232:235], v174 offset:54272
	ds_read_b128 v[236:239], v174 offset:55296
	ds_read_b128 v[240:243], v174 offset:56320
	global_load_lds_dwordx4 v[138:139], off
	s_add_i32 m0, s56, 0x2000
	s_add_u32 s4, s4, 0x100080
	v_lshl_add_u64 v[138:139], v[182:183], 0, s[14:15]
	s_addc_u32 s5, s5, 0
	s_add_i32 s56, s63, s2
	global_load_lds_dwordx4 v[138:139], off
	v_lshl_add_u64 v[138:139], s[4:5], 0, v[134:135]
	s_mov_b32 m0, s56
	s_nop 0
	global_load_lds_dwordx4 v[138:139], off
	v_lshl_add_u64 v[138:139], s[4:5], 0, v[130:131]
	s_add_i32 m0, s56, 0x2000
	s_nop 0
	global_load_lds_dwordx4 v[138:139], off
	v_lshl_add_u64 v[138:139], v[244:245], 0, s[14:15]
	s_mov_b32 m0, s20
	s_nop 0
	global_load_lds_dwordx4 v[138:139], off
	v_lshl_add_u64 v[138:139], v[246:247], 0, s[14:15]
	s_mov_b32 m0, s21
	s_nop 0
	global_load_lds_dwordx4 v[138:139], off
	s_waitcnt vmcnt(8)
	s_waitcnt lgkmcnt(0)
	s_barrier
	s_setprio 1
	s_waitcnt lgkmcnt(0)
	v_mfma_f32_16x16x32_bf16 v[60:63], v[148:151], v[212:215], v[60:63]
	v_mfma_f32_16x16x32_bf16 v[56:59], v[188:191], v[212:215], v[56:59]
	v_mfma_f32_16x16x32_bf16 v[44:47], v[148:151], v[220:223], v[44:47]
	v_mfma_f32_16x16x32_bf16 v[40:43], v[188:191], v[220:223], v[40:43]
	v_mfma_f32_16x16x32_bf16 v[28:31], v[148:151], v[228:231], v[28:31]
	v_mfma_f32_16x16x32_bf16 v[24:27], v[188:191], v[228:231], v[24:27]
	v_mfma_f32_16x16x32_bf16 v[12:15], v[148:151], v[236:239], v[12:15]
	v_mfma_f32_16x16x32_bf16 v[8:11], v[188:191], v[236:239], v[8:11]
	v_mfma_f32_16x16x32_bf16 v[60:63], v[184:187], v[216:219], v[60:63]
	v_mfma_f32_16x16x32_bf16 v[56:59], v[192:195], v[216:219], v[56:59]
	v_mfma_f32_16x16x32_bf16 v[44:47], v[184:187], v[224:227], v[44:47]
	v_mfma_f32_16x16x32_bf16 v[40:43], v[192:195], v[224:227], v[40:43]
	v_mfma_f32_16x16x32_bf16 v[28:31], v[184:187], v[232:235], v[28:31]
	v_mfma_f32_16x16x32_bf16 v[24:27], v[192:195], v[232:235], v[24:27]
	v_mfma_f32_16x16x32_bf16 v[12:15], v[184:187], v[240:243], v[12:15]
	v_mfma_f32_16x16x32_bf16 v[8:11], v[192:195], v[240:243], v[8:11]
	s_setprio 0
	s_setprio 1
	v_mfma_f32_16x16x32_bf16 v[52:55], v[196:199], v[212:215], v[52:55]
	v_mfma_f32_16x16x32_bf16 v[48:51], v[204:207], v[212:215], v[48:51]
	v_mfma_f32_16x16x32_bf16 v[36:39], v[196:199], v[220:223], v[36:39]
	v_mfma_f32_16x16x32_bf16 v[32:35], v[204:207], v[220:223], v[32:35]
	v_mfma_f32_16x16x32_bf16 v[20:23], v[196:199], v[228:231], v[20:23]
	v_mfma_f32_16x16x32_bf16 v[16:19], v[204:207], v[228:231], v[16:19]
	v_mfma_f32_16x16x32_bf16 v[4:7], v[196:199], v[236:239], v[4:7]
	v_mfma_f32_16x16x32_bf16 v[0:3], v[204:207], v[236:239], v[0:3]
	v_mfma_f32_16x16x32_bf16 v[52:55], v[200:203], v[216:219], v[52:55]
	v_mfma_f32_16x16x32_bf16 v[48:51], v[208:211], v[216:219], v[48:51]
	v_mfma_f32_16x16x32_bf16 v[36:39], v[200:203], v[224:227], v[36:39]
	v_mfma_f32_16x16x32_bf16 v[32:35], v[208:211], v[224:227], v[32:35]
	v_mfma_f32_16x16x32_bf16 v[20:23], v[200:203], v[232:235], v[20:23]
	v_mfma_f32_16x16x32_bf16 v[16:19], v[208:211], v[232:235], v[16:19]
	v_mfma_f32_16x16x32_bf16 v[4:7], v[200:203], v[240:243], v[4:7]
	v_mfma_f32_16x16x32_bf16 v[0:3], v[208:211], v[240:243], v[0:3]
	s_setprio 0
	s_add_i32 s61, s61, 2
	s_add_u32 s54, s54, 0x100
	s_addc_u32 s55, s55, 0
	s_add_u32 s59, s59, 0x100
	s_addc_u32 s60, s60, 0
	s_add_u32 s4, s54, 0xfff00080
	s_addc_u32 s5, s55, -1
	s_add_i32 s62, 0, 0x10000
	s_cmp_eq_u32 s61, 60
	s_cselect_b32 s57, s33, s5
	s_cselect_b32 s56, s49, s4
	v_add_u32_e32 v138, s62, v173
	s_cselect_b32 s5, s47, s60
	s_cselect_b32 s4, s58, s59
	s_add_i32 s64, 0, 0x14000
	s_cmp_gt_u32 s61, 61
	s_barrier
	s_cbranch_scc0 .Lkrot_146
	s_and_b64 vcc, exec, s[36:37]
	s_cbranch_vccz .LBB0_149
	s_barrier

.Lkrot_581:
	ds_read_b128 v[130:133], v138
	ds_read_b128 v[134:137], v138 offset:1024
	ds_read_b128 v[158:161], v138 offset:2048
	ds_read_b128 v[162:165], v138 offset:3072
	v_add_u32_e32 v138, s28, v191
	ds_read_b128 v[196:199], v138
	ds_read_b128 v[200:203], v138 offset:1024
	ds_read_b128 v[204:207], v138 offset:2048
	ds_read_b128 v[208:211], v138 offset:3072
	v_lshl_add_u64 v[166:167], s[0:1], 0, v[152:153]
	s_add_i32 m0, s61, 0xc000
	ds_read_b128 v[212:215], v194
	ds_read_b128 v[216:219], v194 offset:1024
	ds_read_b128 v[220:223], v194 offset:2048
	ds_read_b128 v[224:227], v194 offset:3072
	ds_read_b128 v[228:231], v194 offset:4096
	ds_read_b128 v[232:235], v194 offset:5120
	ds_read_b128 v[236:239], v194 offset:6144
	ds_read_b128 v[240:243], v194 offset:7168
	global_load_lds_dwordx4 v[166:167], off
	v_lshl_add_u64 v[166:167], s[0:1], 0, v[154:155]
	s_add_i32 m0, s61, 0xe000
	s_nop 0
	global_load_lds_dwordx4 v[166:167], off
	s_waitcnt vmcnt(8)
	s_waitcnt lgkmcnt(0)
	s_barrier
	s_setprio 1
	s_waitcnt lgkmcnt(0)
	v_mfma_f32_16x16x32_bf16 v[126:129], v[130:133], v[212:215], v[126:129]
	v_mfma_f32_16x16x32_bf16 v[122:125], v[158:161], v[212:215], v[122:125]
	v_mfma_f32_16x16x32_bf16 v[110:113], v[130:133], v[220:223], v[110:113]
	v_mfma_f32_16x16x32_bf16 v[106:109], v[158:161], v[220:223], v[106:109]
	v_mfma_f32_16x16x32_bf16 v[94:97], v[130:133], v[228:231], v[94:97]
	v_mfma_f32_16x16x32_bf16 v[90:93], v[158:161], v[228:231], v[90:93]
	v_mfma_f32_16x16x32_bf16 v[78:81], v[130:133], v[236:239], v[78:81]
	v_mfma_f32_16x16x32_bf16 v[74:77], v[158:161], v[236:239], v[74:77]
	v_mfma_f32_16x16x32_bf16 v[126:129], v[134:137], v[216:219], v[126:129]
	v_mfma_f32_16x16x32_bf16 v[122:125], v[162:165], v[216:219], v[122:125]
	v_mfma_f32_16x16x32_bf16 v[110:113], v[134:137], v[224:227], v[110:113]
	v_mfma_f32_16x16x32_bf16 v[106:109], v[162:165], v[224:227], v[106:109]
	v_mfma_f32_16x16x32_bf16 v[94:97], v[134:137], v[232:235], v[94:97]
	v_mfma_f32_16x16x32_bf16 v[90:93], v[162:165], v[232:235], v[90:93]
	v_mfma_f32_16x16x32_bf16 v[78:81], v[134:137], v[240:243], v[78:81]
	v_mfma_f32_16x16x32_bf16 v[74:77], v[162:165], v[240:243], v[74:77]
	s_setprio 0
	s_setprio 1
	v_mfma_f32_16x16x32_bf16 v[118:121], v[196:199], v[212:215], v[118:121]
	v_mfma_f32_16x16x32_bf16 v[114:117], v[204:207], v[212:215], v[114:117]
	v_mfma_f32_16x16x32_bf16 v[102:105], v[196:199], v[220:223], v[102:105]
	v_mfma_f32_16x16x32_bf16 v[98:101], v[204:207], v[220:223], v[98:101]
	v_mfma_f32_16x16x32_bf16 v[86:89], v[196:199], v[228:231], v[86:89]
	v_mfma_f32_16x16x32_bf16 v[82:85], v[204:207], v[228:231], v[82:85]
	v_mfma_f32_16x16x32_bf16 v[70:73], v[196:199], v[236:239], v[70:73]
	v_mfma_f32_16x16x32_bf16 v[66:69], v[204:207], v[236:239], v[66:69]
	v_mfma_f32_16x16x32_bf16 v[118:121], v[200:203], v[216:219], v[118:121]
	v_mfma_f32_16x16x32_bf16 v[114:117], v[208:211], v[216:219], v[114:117]
	v_mfma_f32_16x16x32_bf16 v[102:105], v[200:203], v[224:227], v[102:105]
	v_mfma_f32_16x16x32_bf16 v[98:101], v[208:211], v[224:227], v[98:101]
	v_mfma_f32_16x16x32_bf16 v[86:89], v[200:203], v[232:235], v[86:89]
	v_mfma_f32_16x16x32_bf16 v[82:85], v[208:211], v[232:235], v[82:85]
	v_mfma_f32_16x16x32_bf16 v[70:73], v[200:203], v[240:243], v[70:73]
	v_mfma_f32_16x16x32_bf16 v[66:69], v[208:211], v[240:243], v[66:69]
	s_setprio 0
	s_barrier
	s_add_i32 s24, s24, s60
	v_lshl_add_u64 v[166:167], s[4:5], 0, v[146:147]
	s_mov_b32 m0, s24
	ds_read_b128 v[212:215], v194 offset:16384
	ds_read_b128 v[216:219], v194 offset:17408
	ds_read_b128 v[220:223], v194 offset:18432
	ds_read_b128 v[224:227], v194 offset:19456
	ds_read_b128 v[228:231], v194 offset:20480
	ds_read_b128 v[232:235], v194 offset:21504
	ds_read_b128 v[236:239], v194 offset:22528
	ds_read_b128 v[240:243], v194 offset:23552
	global_load_lds_dwordx4 v[166:167], off
	s_add_i32 m0, s24, 0x2000
	s_add_u32 s24, s4, 0x40000
	v_lshl_add_u64 v[244:245], s[4:5], 0, v[142:143]
	s_addc_u32 s25, s5, 0
	s_add_i32 s28, s28, s60
	global_load_lds_dwordx4 v[244:245], off
	v_lshl_add_u64 v[246:247], s[24:25], 0, v[146:147]
	s_mov_b32 m0, s28
	v_lshl_add_u64 v[248:249], s[36:37], 0, v[144:145]
	global_load_lds_dwordx4 v[246:247], off
	v_lshl_add_u64 v[246:247], s[24:25], 0, v[142:143]
	s_add_i32 m0, s28, 0x2000
	s_nop 0
	global_load_lds_dwordx4 v[246:247], off
	v_lshl_add_u64 v[246:247], s[36:37], 0, v[148:149]
	s_mov_b32 m0, s61
	s_nop 0
	global_load_lds_dwordx4 v[246:247], off
	s_mov_b32 m0, s62
	s_nop 0
	global_load_lds_dwordx4 v[248:249], off
	s_waitcnt vmcnt(8)
	s_waitcnt lgkmcnt(0)
	s_barrier
	s_setprio 1
	s_waitcnt lgkmcnt(0)
	v_mfma_f32_16x16x32_bf16 v[60:63], v[130:133], v[212:215], v[60:63]
	v_mfma_f32_16x16x32_bf16 v[56:59], v[158:161], v[212:215], v[56:59]
	v_mfma_f32_16x16x32_bf16 v[44:47], v[130:133], v[220:223], v[44:47]
	v_mfma_f32_16x16x32_bf16 v[40:43], v[158:161], v[220:223], v[40:43]
	v_mfma_f32_16x16x32_bf16 v[28:31], v[130:133], v[228:231], v[28:31]
	v_mfma_f32_16x16x32_bf16 v[24:27], v[158:161], v[228:231], v[24:27]
	v_mfma_f32_16x16x32_bf16 v[12:15], v[130:133], v[236:239], v[12:15]
	v_mfma_f32_16x16x32_bf16 v[8:11], v[158:161], v[236:239], v[8:11]
	v_mfma_f32_16x16x32_bf16 v[60:63], v[134:137], v[216:219], v[60:63]
	v_mfma_f32_16x16x32_bf16 v[56:59], v[162:165], v[216:219], v[56:59]
	v_mfma_f32_16x16x32_bf16 v[44:47], v[134:137], v[224:227], v[44:47]
	v_mfma_f32_16x16x32_bf16 v[40:43], v[162:165], v[224:227], v[40:43]
	v_mfma_f32_16x16x32_bf16 v[28:31], v[134:137], v[232:235], v[28:31]
	v_mfma_f32_16x16x32_bf16 v[24:27], v[162:165], v[232:235], v[24:27]
	v_mfma_f32_16x16x32_bf16 v[12:15], v[134:137], v[240:243], v[12:15]
	v_mfma_f32_16x16x32_bf16 v[8:11], v[162:165], v[240:243], v[8:11]
	s_setprio 0
	s_setprio 1
	v_mfma_f32_16x16x32_bf16 v[52:55], v[196:199], v[212:215], v[52:55]
	v_mfma_f32_16x16x32_bf16 v[48:51], v[204:207], v[212:215], v[48:51]
	v_mfma_f32_16x16x32_bf16 v[36:39], v[196:199], v[220:223], v[36:39]
	v_mfma_f32_16x16x32_bf16 v[32:35], v[204:207], v[220:223], v[32:35]
	v_mfma_f32_16x16x32_bf16 v[20:23], v[196:199], v[228:231], v[20:23]
	v_mfma_f32_16x16x32_bf16 v[16:19], v[204:207], v[228:231], v[16:19]
	v_mfma_f32_16x16x32_bf16 v[4:7], v[196:199], v[236:239], v[4:7]
	v_mfma_f32_16x16x32_bf16 v[0:3], v[204:207], v[236:239], v[0:3]
	v_mfma_f32_16x16x32_bf16 v[52:55], v[200:203], v[216:219], v[52:55]
	v_mfma_f32_16x16x32_bf16 v[48:51], v[208:211], v[216:219], v[48:51]
	v_mfma_f32_16x16x32_bf16 v[36:39], v[200:203], v[224:227], v[36:39]
	v_mfma_f32_16x16x32_bf16 v[32:35], v[208:211], v[224:227], v[32:35]
	v_mfma_f32_16x16x32_bf16 v[20:23], v[200:203], v[232:235], v[20:23]
	v_mfma_f32_16x16x32_bf16 v[16:19], v[208:211], v[232:235], v[16:19]
	v_mfma_f32_16x16x32_bf16 v[4:7], v[200:203], v[240:243], v[4:7]
	v_mfma_f32_16x16x32_bf16 v[0:3], v[208:211], v[240:243], v[0:3]
	s_setprio 0
	s_barrier
	s_add_i32 s28, 0, 0x18000
	v_add_u32_e32 v138, s28, v191
	s_add_i32 s29, 0, 0x1c000
	ds_read_b128 v[130:133], v138
	ds_read_b128 v[134:137], v138 offset:1024
	ds_read_b128 v[158:161], v138 offset:2048
	ds_read_b128 v[162:165], v138 offset:3072
	v_add_u32_e32 v138, s29, v191
	ds_read_b128 v[196:199], v138
	ds_read_b128 v[200:203], v138 offset:1024
	ds_read_b128 v[204:207], v138 offset:2048
	ds_read_b128 v[208:211], v138 offset:3072
	s_add_u32 s24, s36, 0x40000
	s_addc_u32 s25, s37, 0
	s_mov_b32 m0, s63
	v_lshl_add_u64 v[182:183], s[24:25], 0, v[148:149]
	ds_read_b128 v[212:215], v194 offset:32768
	ds_read_b128 v[216:219], v194 offset:33792
	ds_read_b128 v[220:223], v194 offset:34816
	ds_read_b128 v[224:227], v194 offset:35840
	ds_read_b128 v[228:231], v194 offset:36864
	ds_read_b128 v[232:235], v194 offset:37888
	ds_read_b128 v[236:239], v194 offset:38912
	ds_read_b128 v[240:243], v194 offset:39936
	global_load_lds_dwordx4 v[182:183], off
	v_lshl_add_u64 v[182:183], s[24:25], 0, v[144:145]
	s_mov_b32 m0, s64
	s_nop 0
	global_load_lds_dwordx4 v[182:183], off
	s_waitcnt vmcnt(8)
	s_waitcnt lgkmcnt(0)
	s_barrier
	s_setprio 1
	s_waitcnt lgkmcnt(0)
	v_mfma_f32_16x16x32_bf16 v[126:129], v[130:133], v[212:215], v[126:129]
	v_mfma_f32_16x16x32_bf16 v[122:125], v[158:161], v[212:215], v[122:125]
	v_mfma_f32_16x16x32_bf16 v[110:113], v[130:133], v[220:223], v[110:113]
	v_mfma_f32_16x16x32_bf16 v[106:109], v[158:161], v[220:223], v[106:109]
	v_mfma_f32_16x16x32_bf16 v[94:97], v[130:133], v[228:231], v[94:97]
	v_mfma_f32_16x16x32_bf16 v[90:93], v[158:161], v[228:231], v[90:93]
	v_mfma_f32_16x16x32_bf16 v[78:81], v[130:133], v[236:239], v[78:81]
	v_mfma_f32_16x16x32_bf16 v[74:77], v[158:161], v[236:239], v[74:77]
	v_mfma_f32_16x16x32_bf16 v[126:129], v[134:137], v[216:219], v[126:129]
	v_mfma_f32_16x16x32_bf16 v[122:125], v[162:165], v[216:219], v[122:125]
	v_mfma_f32_16x16x32_bf16 v[110:113], v[134:137], v[224:227], v[110:113]
	v_mfma_f32_16x16x32_bf16 v[106:109], v[162:165], v[224:227], v[106:109]
	v_mfma_f32_16x16x32_bf16 v[94:97], v[134:137], v[232:235], v[94:97]
	v_mfma_f32_16x16x32_bf16 v[90:93], v[162:165], v[232:235], v[90:93]
	v_mfma_f32_16x16x32_bf16 v[78:81], v[134:137], v[240:243], v[78:81]
	v_mfma_f32_16x16x32_bf16 v[74:77], v[162:165], v[240:243], v[74:77]
	s_setprio 0
	s_setprio 1
	v_mfma_f32_16x16x32_bf16 v[118:121], v[196:199], v[212:215], v[118:121]
	v_mfma_f32_16x16x32_bf16 v[114:117], v[204:207], v[212:215], v[114:117]
	v_mfma_f32_16x16x32_bf16 v[102:105], v[196:199], v[220:223], v[102:105]
	v_mfma_f32_16x16x32_bf16 v[98:101], v[204:207], v[220:223], v[98:101]
	v_mfma_f32_16x16x32_bf16 v[86:89], v[196:199], v[228:231], v[86:89]
	v_mfma_f32_16x16x32_bf16 v[82:85], v[204:207], v[228:231], v[82:85]
	v_mfma_f32_16x16x32_bf16 v[70:73], v[196:199], v[236:239], v[70:73]
	v_mfma_f32_16x16x32_bf16 v[66:69], v[204:207], v[236:239], v[66:69]
	v_mfma_f32_16x16x32_bf16 v[118:121], v[200:203], v[216:219], v[118:121]
	v_mfma_f32_16x16x32_bf16 v[114:117], v[208:211], v[216:219], v[114:117]
	v_mfma_f32_16x16x32_bf16 v[102:105], v[200:203], v[224:227], v[102:105]
	v_mfma_f32_16x16x32_bf16 v[98:101], v[208:211], v[224:227], v[98:101]
	v_mfma_f32_16x16x32_bf16 v[86:89], v[200:203], v[232:235], v[86:89]
	v_mfma_f32_16x16x32_bf16 v[82:85], v[208:211], v[232:235], v[82:85]
	v_mfma_f32_16x16x32_bf16 v[70:73], v[200:203], v[240:243], v[70:73]
	v_mfma_f32_16x16x32_bf16 v[66:69], v[208:211], v[240:243], v[66:69]
	s_setprio 0
	s_barrier
	s_add_i32 s24, s28, s60
	v_lshl_add_u64 v[166:167], v[166:167], 0, s[14:15]
	s_mov_b32 m0, s24
	ds_read_b128 v[212:215], v194 offset:49152
	ds_read_b128 v[216:219], v194 offset:50176
	ds_read_b128 v[220:223], v194 offset:51200
	ds_read_b128 v[224:227], v194 offset:52224
	ds_read_b128 v[228:231], v194 offset:53248
	ds_read_b128 v[232:235], v194 offset:54272
	ds_read_b128 v[236:239], v194 offset:55296
	ds_read_b128 v[240:243], v194 offset:56320
	global_load_lds_dwordx4 v[166:167], off
	s_add_i32 m0, s24, 0x2000
	s_add_u32 s4, s4, 0x40080
	v_lshl_add_u64 v[166:167], v[244:245], 0, s[14:15]
	s_addc_u32 s5, s5, 0
	s_add_i32 s24, s29, s60
	global_load_lds_dwordx4 v[166:167], off
	v_lshl_add_u64 v[166:167], s[4:5], 0, v[146:147]
	s_mov_b32 m0, s24
	s_nop 0
	global_load_lds_dwordx4 v[166:167], off
	v_lshl_add_u64 v[166:167], s[4:5], 0, v[142:143]
	s_add_i32 m0, s24, 0x2000
	s_nop 0
	global_load_lds_dwordx4 v[166:167], off
	v_lshl_add_u64 v[166:167], v[246:247], 0, s[14:15]
	s_mov_b32 m0, s65
	s_nop 0
	global_load_lds_dwordx4 v[166:167], off
	v_lshl_add_u64 v[166:167], v[248:249], 0, s[14:15]
	s_mov_b32 m0, s70
	s_nop 0
	global_load_lds_dwordx4 v[166:167], off
	s_waitcnt vmcnt(8)
	s_waitcnt lgkmcnt(0)
	s_barrier
	s_setprio 1
	s_waitcnt lgkmcnt(0)
	v_mfma_f32_16x16x32_bf16 v[60:63], v[130:133], v[212:215], v[60:63]
	v_mfma_f32_16x16x32_bf16 v[56:59], v[158:161], v[212:215], v[56:59]
	v_mfma_f32_16x16x32_bf16 v[44:47], v[130:133], v[220:223], v[44:47]
	v_mfma_f32_16x16x32_bf16 v[40:43], v[158:161], v[220:223], v[40:43]
	v_mfma_f32_16x16x32_bf16 v[28:31], v[130:133], v[228:231], v[28:31]
	v_mfma_f32_16x16x32_bf16 v[24:27], v[158:161], v[228:231], v[24:27]
	v_mfma_f32_16x16x32_bf16 v[12:15], v[130:133], v[236:239], v[12:15]
	v_mfma_f32_16x16x32_bf16 v[8:11], v[158:161], v[236:239], v[8:11]
	v_mfma_f32_16x16x32_bf16 v[60:63], v[134:137], v[216:219], v[60:63]
	v_mfma_f32_16x16x32_bf16 v[56:59], v[162:165], v[216:219], v[56:59]
	v_mfma_f32_16x16x32_bf16 v[44:47], v[134:137], v[224:227], v[44:47]
	v_mfma_f32_16x16x32_bf16 v[40:43], v[162:165], v[224:227], v[40:43]
	v_mfma_f32_16x16x32_bf16 v[28:31], v[134:137], v[232:235], v[28:31]
	v_mfma_f32_16x16x32_bf16 v[24:27], v[162:165], v[232:235], v[24:27]
	v_mfma_f32_16x16x32_bf16 v[12:15], v[134:137], v[240:243], v[12:15]
	v_mfma_f32_16x16x32_bf16 v[8:11], v[162:165], v[240:243], v[8:11]
	s_setprio 0
	s_setprio 1
	v_mfma_f32_16x16x32_bf16 v[52:55], v[196:199], v[212:215], v[52:55]
	v_mfma_f32_16x16x32_bf16 v[48:51], v[204:207], v[212:215], v[48:51]
	v_mfma_f32_16x16x32_bf16 v[36:39], v[196:199], v[220:223], v[36:39]
	v_mfma_f32_16x16x32_bf16 v[32:35], v[204:207], v[220:223], v[32:35]
	v_mfma_f32_16x16x32_bf16 v[20:23], v[196:199], v[228:231], v[20:23]
	v_mfma_f32_16x16x32_bf16 v[16:19], v[204:207], v[228:231], v[16:19]
	v_mfma_f32_16x16x32_bf16 v[4:7], v[196:199], v[236:239], v[4:7]
	v_mfma_f32_16x16x32_bf16 v[0:3], v[204:207], v[236:239], v[0:3]
	v_mfma_f32_16x16x32_bf16 v[52:55], v[200:203], v[216:219], v[52:55]
	v_mfma_f32_16x16x32_bf16 v[48:51], v[208:211], v[216:219], v[48:51]
	v_mfma_f32_16x16x32_bf16 v[36:39], v[200:203], v[224:227], v[36:39]
	v_mfma_f32_16x16x32_bf16 v[32:35], v[208:211], v[224:227], v[32:35]
	v_mfma_f32_16x16x32_bf16 v[20:23], v[200:203], v[232:235], v[20:23]
	v_mfma_f32_16x16x32_bf16 v[16:19], v[208:211], v[232:235], v[16:19]
	v_mfma_f32_16x16x32_bf16 v[4:7], v[200:203], v[240:243], v[4:7]
	v_mfma_f32_16x16x32_bf16 v[0:3], v[208:211], v[240:243], v[0:3]
	s_setprio 0
	s_add_i32 s21, s21, 2
	s_add_u32 s0, s0, 0x100
	s_addc_u32 s1, s1, 0
	s_add_u32 s19, s19, 0x100
	s_addc_u32 s20, s20, 0
	s_add_u32 s4, s0, 0xfffc0080
	s_addc_u32 s5, s1, -1
	s_add_i32 s24, 0, 0x10000
	s_cmp_eq_u32 s21, 12
	s_cselect_b32 s37, s8, s5
	s_cselect_b32 s36, s9, s4
	v_add_u32_e32 v138, s24, v191
	s_cselect_b32 s5, s10, s20
	s_cselect_b32 s4, s18, s19
	s_add_i32 s28, 0, 0x14000
	s_cmp_gt_u32 s21, 13
	s_barrier
	s_cbranch_scc0 .Lkrot_581
	s_and_b64 vcc, exec, s[40:41]
	s_cbranch_vccz .LBB0_584
	s_barrier
